# DSA: histogram zeroed in previous item's attention part; per-item set-up barrier kept only for the first item (on top of v13)
# speedup vs baseline: 1.0005x; 1.0005x over previous
; template <bool DUMMY> __device__ __forceinline__ void phase_dsa(const Args& a, unsigned char* lds) {
;     ...
;     if ((int)blockIdx.x < 16384) DSA_LOAD_ITEM(blockIdx.x);
;     for (int item = blockIdx.x; item < 16384; item += gridDim.x) {
;         int tid_ = threadIdx.x; asm volatile("" : "+v"(tid_));
;         const int tid = tid_, wave = __builtin_amdgcn_readfirstlane(tid >> 6), lane = tid & 63, quad = lane >> 4, l15 = lane & 15;
;         const int b = item & 7, tq = item >> 3, t0 = tq * 4, L = ((t0 >> 6) + 1) * 64;
;         const size_t r0 = (size_t)b * SEQ + t0;
;         const bool do_sel = (L > 256) && !DBG_NOSEL;
;         { u32x4* hz = (u32x4*)HIST; hz[tid] = (u32x4){0u, 0u, 0u, 0u}; hz[tid + 512] = (u32x4){0u, 0u, 0u, 0u}; }
;         if (tid < 8) CNT[4 + tid] = 0;
;         QS[tid] = qsv[0]; QS[tid + 512] = qsv[1];
.LBB0_858:
	s_mov_b32 s92, 1
	s_mov_b32 s4, 0
	s_mov_b32 s6, s4
	s_mov_b32 s7, s4
	s_add_u32 s19, s70, 0x34800000
	s_mov_b32 s5, s4
	v_mov_b64_e32 v[248:249], s[6:7]
	v_mov_b32_e32 v9, 0
	v_mbcnt_hi_u32_b32 v218, -1, v157
	s_addc_u32 s36, s71, 0
	v_mov_b64_e32 v[246:247], s[4:5]
	s_add_i32 s37, 0, 0x26080
	s_movk_i32 s38, 0x2800
	s_movk_i32 s39, 0xff
	s_movk_i32 s40, 0x100
	s_mov_b32 s41, 0x8020
	s_movk_i32 s42, 0x1c1
	s_movk_i32 s43, 0x1c0
	s_movk_i32 s48, 0xbf
	v_mov_b32_e32 v159, 1
	s_mov_b32 s49, 0x7ffffeff
	v_mov_b32_e32 v216, 0x100
	s_movk_i32 s50, 0x90
	s_mov_b32 s18, 0x3e000000
	s_mov_b32 s51, 0xff800000
	v_mov_b32_e32 v217, 0x10000
	v_and_b32_e32 v219, 64, v218
	v_mov_b32_e32 v250, v9
	v_mov_b32_e32 v251, v9
	s_mov_b32 s52, s2
	s_branch .LBB0_860

; #define IDX_LOAD(BUF, G) do { _Pragma("unroll") for (int tt = 0; tt < 4; ++tt) _Pragma("unroll") for (int ks = 0; ks < 2; ++ks) \
;                 BUF[tt][ks] = *(const bf16x8*)(ikb + (size_t)(((G) * 4 + tt) * 8 + ks * 4) * 128); } while (0)
; template <bool DUMMY> __device__ __forceinline__ void phase_dsa(const Args& a, unsigned char* lds) {
;     ...
;         const int tid = tid_, wave = __builtin_amdgcn_readfirstlane(tid >> 6), lane = tid & 63, quad = lane >> 4, l15 = lane & 15;
;         const int b = item & 7, tq = item >> 3, t0 = tq * 4, L = ((t0 >> 6) + 1) * 64;
;         const size_t r0 = (size_t)b * SEQ + t0;
;         const bool do_sel = (L > 256) && !DBG_NOSEL;
;         { u32x4* hz = (u32x4*)HIST; hz[tid] = (u32x4){0u, 0u, 0u, 0u}; hz[tid + 512] = (u32x4){0u, 0u, 0u, 0u}; }
;         if (tid < 8) CNT[4 + tid] = 0;
;         QS[tid] = qsv[0]; QS[tid + 512] = qsv[1];
;         float wq[8];
; #pragma unroll
;         for (int h = 0; h < 4; ++h) { wq[h] = wqv[0][h] * idx_scale; wq[4 + h] = wqv[1][h] * idx_scale; }
;         bf16x8 af[2][2];
; #pragma unroll
;         for (int T = 0; T < 2; ++T)
; #pragma unroll
;             for (int ks = 0; ks < 2; ++ks) af[T][ks] = *(const bf16x8*)(P + (r0 + (l15 >> 2)) * LDP + C_IQ + (4 * T + (l15 & 3)) * 64 + ks * 32 + quad * 8);
;         const int ngroups = L >> 6;
;         const bf16_t* ikb = IKC + (size_t)b * SEQ * 64 + (quad * 16 + l15) * 8;
;         bf16x8 B0[4][2], B1[4][2], B2[4][2];
;     ...
;         if (wave < ngroups) IDX_LOAD(B0, wave);
;         if (wave + 8 < ngroups) IDX_LOAD(B1, wave + 8);
;         if (wave + 16 < ngroups) IDX_LOAD(B2, wave + 16);
.LBB0_860:
	s_waitcnt vmcnt(3)
	v_mov_b32_e32 v124, v156
	s_nop 0
	v_lshl_add_u32 v8, v124, 4, 0
	v_readfirstlane_b32 s62, v124
	v_add_u32_e32 v8, 0x20080, v8
	v_cmp_gt_i32_e32 vcc, 8, v124
	s_cmp_eq_u32 s92, 0
	s_cbranch_scc1 .Ldsa_nz
	ds_write_b128 v8, v[246:249]
	ds_write_b128 v8, v[246:249] offset:8192
.Ldsa_nz:
	s_and_saveexec_b64 s[0:1], vcc
	v_lshl_add_u32 v8, v124, 2, s37
	ds_write_b32 v8, v9 offset:16
	s_or_b64 exec, exec, s[0:1]
	s_ashr_i32 s22, s52, 1
	s_and_b32 s0, s22, -4
	s_andn2_b32 s22, s22, 63
	s_lshl_b32 s1, s52, 13
	s_ashr_i32 s63, s62, 6
	s_add_i32 s12, s22, 64
	s_and_b32 s64, s1, 0xe000
	s_ashr_i32 s4, s0, 31
	s_add_u32 s53, s64, s0
	v_bfe_u32 v8, v124, 2, 2
	v_or_b32_e32 v8, s53, v8
	v_mov_b64_e32 v[10:11], s[44:45]
	v_mad_i64_i32 v[10:11], s[0:1], v8, s38, v[10:11]
	v_and_b32_e32 v8, 48, v124
	v_lshl_add_u64 v[10:11], v[10:11], 0, v[8:9]
	v_lshlrev_b32_e32 v8, 7, v124
	v_and_b32_e32 v8, 0x180, v8
	v_lshl_add_u64 v[10:11], v[10:11], 0, v[8:9]
	global_load_dwordx4 v[108:111], v[10:11], off offset:1536
	global_load_dwordx4 v[112:115], v[10:11], off offset:1600
	global_load_dwordx4 v[116:119], v[10:11], off offset:2048
	global_load_dwordx4 v[120:123], v[10:11], off offset:2112
	s_addc_u32 s60, 0, s4
	v_lshl_add_u32 v8, v124, 2, 0
	s_ashr_i32 s13, s12, 6
	s_lshl_b32 s0, s64, 7
	v_add_u32_e32 v8, 0x25080, v8
	s_add_u32 s0, s56, s0
	s_waitcnt vmcnt(4)
	ds_write2st64_b32 v8, v220, v221 offset1:8
	s_addc_u32 s1, s57, 0
	v_lshlrev_b32_e32 v8, 4, v124
	v_and_b32_e32 v8, 0x3f0, v8
	s_cmp_lt_i32 s63, s13
	s_cselect_b64 s[4:5], -1, 0
	s_cmp_ge_i32 s63, s13
	v_lshl_add_u64 v[10:11], s[0:1], 0, v[8:9]
	s_cbranch_scc1 .LBB0_902
	s_lshl_b32 s0, s63, 5
	s_ashr_i32 s1, s0, 31
	s_lshl_b64 s[6:7], s[0:1], 8
	v_lshl_add_u64 v[12:13], v[10:11], 0, s[6:7]
	s_or_b32 s6, s0, 4
	s_ashr_i32 s7, s6, 31
	s_lshl_b64 s[6:7], s[6:7], 8
	v_lshl_add_u64 v[32:33], v[10:11], 0, s[6:7]
	s_or_b32 s6, s0, 8
	s_ashr_i32 s7, s6, 31
	s_lshl_b64 s[6:7], s[6:7], 8
	v_lshl_add_u64 v[52:53], v[10:11], 0, s[6:7]
	s_or_b32 s6, s0, 12
	s_ashr_i32 s7, s6, 31
	s_lshl_b64 s[6:7], s[6:7], 8
	v_lshl_add_u64 v[56:57], v[10:11], 0, s[6:7]
	s_or_b32 s6, s0, 16
	s_ashr_i32 s7, s6, 31
	s_lshl_b64 s[6:7], s[6:7], 8
	v_lshl_add_u64 v[76:77], v[10:11], 0, s[6:7]
	s_or_b32 s6, s0, 20
	s_ashr_i32 s7, s6, 31
	s_lshl_b64 s[6:7], s[6:7], 8
	v_lshl_add_u64 v[80:81], v[10:11], 0, s[6:7]
	s_or_b32 s6, s0, 24
	s_or_b32 s0, s0, 28
	s_ashr_i32 s7, s6, 31
	s_ashr_i32 s1, s0, 31
	s_lshl_b64 s[6:7], s[6:7], 8
	s_lshl_b64 s[0:1], s[0:1], 8
	v_lshl_add_u64 v[100:101], v[10:11], 0, s[6:7]
	v_lshl_add_u64 v[104:105], v[10:11], 0, s[0:1]
	global_load_dwordx4 v[12:15], v[12:13], off
	s_nop 0
	global_load_dwordx4 v[32:35], v[32:33], off
	s_nop 0
	global_load_dwordx4 v[52:55], v[52:53], off
	s_nop 0
	global_load_dwordx4 v[56:59], v[56:57], off
	s_nop 0
	global_load_dwordx4 v[76:79], v[76:77], off
	s_nop 0
	global_load_dwordx4 v[80:83], v[80:81], off
	s_nop 0
	global_load_dwordx4 v[100:103], v[100:101], off
	s_nop 0
	global_load_dwordx4 v[104:107], v[104:105], off
	s_add_i32 s0, s63, 8
	s_cmp_ge_i32 s0, s13
	s_cbranch_scc0 .LBB0_903

; __device__ __forceinline__ void lds_fence() { asm volatile("s_waitcnt lgkmcnt(0)" ::: "memory"); }
; #define IDX_LOAD(BUF, G) do { _Pragma("unroll") for (int tt = 0; tt < 4; ++tt) _Pragma("unroll") for (int ks = 0; ks < 2; ++ks) \
;                 BUF[tt][ks] = *(const bf16x8*)(ikb + (size_t)(((G) * 4 + tt) * 8 + ks * 4) * 128); } while (0)
; template <bool DUMMY> __device__ __forceinline__ void phase_dsa(const Args& a, unsigned char* lds) {
;     ...
;         for (int h = 0; h < 4; ++h) { wq[h] = wqv[0][h] * idx_scale; wq[4 + h] = wqv[1][h] * idx_scale; }
;         bf16x8 af[2][2];
; #pragma unroll
;         for (int T = 0; T < 2; ++T)
; #pragma unroll
;             for (int ks = 0; ks < 2; ++ks) af[T][ks] = *(const bf16x8*)(P + (r0 + (l15 >> 2)) * LDP + C_IQ + (4 * T + (l15 & 3)) * 64 + ks * 32 + quad * 8);
;         const int ngroups = L >> 6;
;         const bf16_t* ikb = IKC + (size_t)b * SEQ * 64 + (quad * 16 + l15) * 8;
;         bf16x8 B0[4][2], B1[4][2], B2[4][2];
;     ...
;         if (wave < ngroups) IDX_LOAD(B0, wave);
;         if (wave + 8 < ngroups) IDX_LOAD(B1, wave + 8);
;         if (wave + 16 < ngroups) IDX_LOAD(B2, wave + 16);
;         lds_fence(); __builtin_amdgcn_s_barrier();
;         for (int rep = 0; rep < ((DBG_TWICE & 2) ? 2 : 1); ++rep) {
;             const bool hist_on = do_sel && (rep == (((DBG_TWICE & 2) ? 2 : 1) - 1));
;     ...
;             int g = wave;
;             for (; g < ngroups; g += 24) {
.LBB0_866:
	s_cmpk_gt_i32 s22, 0xff
	s_waitcnt lgkmcnt(0)
	s_cselect_b64 s[6:7], -1, 0
	s_cmpk_lt_i32 s22, 0x100
	v_and_b32_e32 v125, 15, v124
	s_cselect_b64 s[0:1], -1, 0
	s_andn2_b64 vcc, exec, s[4:5]
	s_cmp_eq_u32 s92, 0
	s_cbranch_scc1 .Ldsa_nb
	s_barrier
	s_mov_b32 s92, 0
.Ldsa_nb:
	s_cbranch_vccnz .LBB0_904
	s_lshl_b32 s4, s63, 5
	s_add_i32 s8, s4, 0x51c
	s_lshl_b32 s4, s63, 8
	v_bfe_u32 v8, v124, 4, 2
	v_mov_b32_e32 v134, s4
	v_mad_u32_u24 v134, v8, s41, v134
	v_lshlrev_b32_e32 v135, 2, v125
	v_mul_f32_e32 v126, 0x3d3504f3, v4
	v_mul_f32_e32 v127, 0x3d3504f3, v0
	v_mul_f32_e32 v128, 0x3d3504f3, v5
	v_mul_f32_e32 v129, 0x3d3504f3, v1
	v_mul_f32_e32 v130, 0x3d3504f3, v6
	v_mul_f32_e32 v131, 0x3d3504f3, v2
	v_mul_f32_e32 v132, 0x3d3504f3, v7
	v_mul_f32_e32 v133, 0x3d3504f3, v3
	v_add3_u32 v134, v134, v135, 0
	s_mov_b32 s9, s63

; __device__ __forceinline__ void lds_fence() { asm volatile("s_waitcnt lgkmcnt(0)" ::: "memory"); }
; template <bool DUMMY> __device__ __forceinline__ void phase_dsa(const Args& a, unsigned char* lds) {
;     ...
;         lds_fence(); __builtin_amdgcn_s_barrier();
;         for (int repc = 0; repc < ((DBG_TWICE & 4) ? 2 : 1); ++repc) {
;             const bool dummy_c = (repc + 1) < ((DBG_TWICE & 4) ? 2 : 1);
;             int lane_c = lane; asm volatile("" : "+v"(lane_c));
;             const int qi = wave >> 1, g = wave & 1; const int count = CNT[qi];
;             const int* list = LIST + qi * 256;
;             float* PB = SC + wave * 1024;
;             const unsigned* qd = QS + (qi * 8 + g * 4) * 32;
;             const bf16_t* kvb = KVC + (size_t)b * SEQ * 256 + g * 64;
;             const int ks = lane_c >> 3, dg = lane_c & 7, l15c = lane_c & 15, quadc = lane_c >> 4;
;             const int nblk = count >> 6;
;             bf16_t* KL = (bf16_t*)(lds + 32768 + wave * 9216);
;             bf16x8 bq[2];
; #pragma unroll
;             for (int s2 = 0; s2 < 2; ++s2) {
;                 bf16x8 t = *(const bf16x8*)((const bf16_t*)QS + (qi * 8 + g * 4 + (l15c & 3)) * 64 + s2 * 32 + quadc * 8);
;                 if (l15c >= 4) t = (bf16x8){0, 0, 0, 0, 0, 0, 0, 0};
;                 bq[s2] = t;
;             }
;             const bf16_t* kb = kvb + dg * 8;
;             float sreg[4][4][4];
;             u32x4 kcur[8];
; #pragma unroll
;             for (int u = 0; u < 8; ++u) kcur[u] = *(const u32x4*)(kb + (size_t)list[u * 8 + ks] * 256);
.LBB0_1069:
	s_waitcnt lgkmcnt(0)
	s_barrier
	v_lshlrev_b32_e32 v12, 4, v156
	v_add_u32_e32 v12, 0x20080, v12
	ds_write_b128 v12, v[246:249]
	ds_write_b128 v12, v[246:249] offset:8192
	s_add_i32 s7, s65, 0
	v_ashrrev_i32_e32 v225, 3, v222
	v_lshl_add_u32 v8, v225, 2, s7
	v_add_u32_e32 v224, 0x24080, v8
	ds_read2_b32 v[10:11], v224 offset1:8
	s_lshl_b32 s1, s61, 2
	s_bfe_u32 s0, s62, 0x10006
	s_add_i32 s1, s1, 0
	s_mulk_i32 s63, 0x2400
	s_add_i32 s4, s1, 0x26080
	s_lshl_b32 s5, s61, 3
	s_lshl_b32 s10, s0, 2
	s_lshl_b32 s1, s64, 9
	s_add_i32 s11, s63, 0
	s_add_i32 s6, 0, 0x25080
	s_add_u32 s1, s19, s1
	s_addc_u32 s7, s36, 0
	s_lshl_b32 s0, s0, 7
	s_waitcnt vmcnt(3) lgkmcnt(0)
	v_ashrrev_i32_e32 v109, 31, v10
	v_mov_b32_e32 v108, v10
	v_ashrrev_i32_e32 v111, 31, v11
	v_mov_b32_e32 v110, v11
	ds_read2_b32 v[10:11], v224 offset0:16 offset1:24
	s_add_u32 s0, s1, s0
	v_lshlrev_b32_e32 v8, 4, v222
	s_addc_u32 s1, s7, 0
	v_and_b32_e32 v8, 0x70, v8
	v_lshl_add_u64 v[160:161], s[0:1], 0, v[8:9]
	v_lshlrev_b64 v[108:109], 9, v[108:109]
	v_lshlrev_b64 v[110:111], 9, v[110:111]
	v_lshl_add_u64 v[108:109], v[160:161], 0, v[108:109]
	v_lshl_add_u64 v[110:111], v[160:161], 0, v[110:111]
	global_load_dwordx4 v[116:119], v[108:109], off
	global_load_dwordx4 v[120:123], v[110:111], off
	s_waitcnt lgkmcnt(0)
	v_ashrrev_i32_e32 v109, 31, v10
	v_mov_b32_e32 v108, v10
	v_ashrrev_i32_e32 v111, 31, v11
	v_mov_b32_e32 v110, v11
	ds_read2_b32 v[10:11], v224 offset0:32 offset1:40
	v_lshlrev_b64 v[108:109], 9, v[108:109]
	v_lshlrev_b64 v[110:111], 9, v[110:111]
	v_lshl_add_u64 v[108:109], v[160:161], 0, v[108:109]
	v_lshl_add_u64 v[110:111], v[160:161], 0, v[110:111]
	global_load_dwordx4 v[124:127], v[108:109], off
	global_load_dwordx4 v[128:131], v[110:111], off
	s_waitcnt lgkmcnt(0)
	v_ashrrev_i32_e32 v109, 31, v10
	v_mov_b32_e32 v108, v10
	v_ashrrev_i32_e32 v111, 31, v11
	v_mov_b32_e32 v110, v11
	ds_read2_b32 v[10:11], v224 offset0:48 offset1:56
	v_lshlrev_b64 v[108:109], 9, v[108:109]
	v_lshl_add_u64 v[108:109], v[160:161], 0, v[108:109]
	v_lshlrev_b64 v[110:111], 9, v[110:111]
	v_lshl_add_u64 v[110:111], v[160:161], 0, v[110:111]
	global_load_dwordx4 v[132:135], v[108:109], off
	global_load_dwordx4 v[136:139], v[110:111], off
	s_waitcnt lgkmcnt(0)
	v_ashrrev_i32_e32 v109, 31, v10
	v_mov_b32_e32 v108, v10
	v_lshlrev_b64 v[108:109], 9, v[108:109]
	v_ashrrev_i32_e32 v111, 31, v11
	v_mov_b32_e32 v110, v11
	v_lshl_add_u64 v[108:109], v[160:161], 0, v[108:109]
	v_lshlrev_b64 v[10:11], 9, v[110:111]
	v_lshl_add_u64 v[10:11], v[160:161], 0, v[10:11]
	global_load_dwordx4 v[140:143], v[108:109], off
	global_load_dwordx4 v[144:147], v[10:11], off
	v_and_or_b32 v11, v222, 3, s5
	v_or_b32_e32 v11, s10, v11
	v_lshlrev_b32_e32 v11, 7, v11
	v_and_b32_e32 v152, -16, v222
	v_mov_b32_e32 v10, s4
	v_add3_u32 v11, s6, v11, v152
	ds_read_b128 v[108:111], v11
	ds_read_b32 v10, v10
	ds_read_b128 v[148:151], v11 offset:64
	v_and_b32_e32 v223, 15, v222
	v_cmp_lt_u32_e32 vcc, 3, v223
	v_add_u32_e32 v158, s11, v8
	s_waitcnt lgkmcnt(1)
	v_readfirstlane_b32 s0, v10
	s_ashr_i32 s12, s0, 6
	s_cmp_gt_i32 s12, 0
	s_waitcnt vmcnt(10)
	v_cndmask_b32_e64 v115, v111, 0, vcc
	v_cndmask_b32_e64 v114, v110, 0, vcc
	v_cndmask_b32_e64 v113, v109, 0, vcc
	v_cndmask_b32_e64 v112, v108, 0, vcc
	s_waitcnt lgkmcnt(0)
	v_cndmask_b32_e64 v111, v151, 0, vcc
	v_cndmask_b32_e64 v110, v150, 0, vcc
	v_cndmask_b32_e64 v109, v149, 0, vcc
	v_cndmask_b32_e64 v108, v148, 0, vcc
	s_cselect_b64 s[0:1], -1, 0
	s_cmp_lt_i32 s12, 1
	v_add_u32_e32 v226, s11, v152
	s_cbranch_scc1 .LBB0_1073
	v_mad_u64_u32 v[10:11], s[4:5], v225, s50, v[158:159]
	s_cmp_eq_u32 s12, 1
	s_waitcnt vmcnt(7)
	ds_write_b128 v10, v[116:119] offset:32768
	s_waitcnt vmcnt(6)
	ds_write_b128 v10, v[120:123] offset:33920
	s_waitcnt vmcnt(5)
	ds_write_b128 v10, v[124:127] offset:35072
	s_waitcnt vmcnt(4)
	ds_write_b128 v10, v[128:131] offset:36224
	s_waitcnt vmcnt(3)
	ds_write_b128 v10, v[132:135] offset:37376
	s_waitcnt vmcnt(2)
	ds_write_b128 v10, v[136:139] offset:38528
	s_waitcnt vmcnt(1)
	ds_write_b128 v10, v[140:143] offset:39680
	s_waitcnt vmcnt(0)
	ds_write_b128 v10, v[144:147] offset:40832
	s_cbranch_scc1 .LBB0_1072
	ds_read2_b32 v[10:11], v224 offset0:64 offset1:72
	ds_read2_b32 v[124:125], v224 offset0:80 offset1:88
	s_waitcnt lgkmcnt(1)
	v_ashrrev_i32_e32 v117, 31, v10
	v_mov_b32_e32 v116, v10
	v_ashrrev_i32_e32 v119, 31, v11
	v_mov_b32_e32 v118, v11
	v_lshlrev_b64 v[10:11], 9, v[116:117]
	v_lshlrev_b64 v[116:117], 9, v[118:119]
	v_lshl_add_u64 v[10:11], v[160:161], 0, v[10:11]
	v_lshl_add_u64 v[120:121], v[160:161], 0, v[116:117]
	global_load_dwordx4 v[116:119], v[10:11], off
	s_nop 0
	global_load_dwordx4 v[120:123], v[120:121], off
	s_waitcnt lgkmcnt(0)
	v_ashrrev_i32_e32 v11, 31, v124
	v_mov_b32_e32 v10, v124
	v_ashrrev_i32_e32 v127, 31, v125
	v_mov_b32_e32 v126, v125
	ds_read2_b32 v[132:133], v224 offset0:96 offset1:104
	v_lshlrev_b64 v[10:11], 9, v[10:11]
	v_lshlrev_b64 v[124:125], 9, v[126:127]
	v_lshl_add_u64 v[10:11], v[160:161], 0, v[10:11]
	v_lshl_add_u64 v[128:129], v[160:161], 0, v[124:125]
	global_load_dwordx4 v[124:127], v[10:11], off
	s_nop 0
	global_load_dwordx4 v[128:131], v[128:129], off
	ds_read2_b32 v[140:141], v224 offset0:112 offset1:120
	s_waitcnt lgkmcnt(1)
	v_ashrrev_i32_e32 v11, 31, v132
	v_mov_b32_e32 v10, v132
	v_ashrrev_i32_e32 v135, 31, v133
	v_mov_b32_e32 v134, v133
	v_lshlrev_b64 v[10:11], 9, v[10:11]
	v_lshlrev_b64 v[132:133], 9, v[134:135]
	v_lshl_add_u64 v[10:11], v[160:161], 0, v[10:11]
	v_lshl_add_u64 v[136:137], v[160:161], 0, v[132:133]
	global_load_dwordx4 v[132:135], v[10:11], off
	s_nop 0
	global_load_dwordx4 v[136:139], v[136:137], off
	s_waitcnt lgkmcnt(0)
	v_ashrrev_i32_e32 v11, 31, v140
	v_mov_b32_e32 v10, v140
	v_ashrrev_i32_e32 v143, 31, v141
	v_mov_b32_e32 v142, v141
	v_lshlrev_b64 v[10:11], 9, v[10:11]
	v_lshlrev_b64 v[140:141], 9, v[142:143]
	v_lshl_add_u64 v[10:11], v[160:161], 0, v[10:11]
	v_lshl_add_u64 v[144:145], v[160:161], 0, v[140:141]
	global_load_dwordx4 v[140:143], v[10:11], off
	s_nop 0
	global_load_dwordx4 v[144:147], v[144:145], off
